# P3 loop: p0-chain gap work rebalanced (base + V-address adds behind MFMA 1, block rebuild behind MFMAs 2-3, V reads behind MFMA 4)
# baseline (speedup 1.0000x reference)
.LBB0_325:
	s_waitcnt lgkmcnt(4)
	v_mfma_f32_32x32x16_bf16 v[96:111], v[80:83], v[144:147], v[64:79]
	s_add_i32 s4, s100, 64
	v_cvt_f32_i32_e32 v156, s4
	v_add_f32_e32 v156, v255, v156
	v_fma_f32 v254, v208, v156, -v207
	s_add_i32 s3, s79, 0xfffe8000
	s_and_b32 s3, s3, 0x18000
	v_add_u32_e32 v158, s3, v235
	v_add_u32_e32 v159, s3, v239
	v_add_u32_e32 v160, s3, v236
	v_add_u32_e32 v161, s3, v234
	v_mfma_f32_32x32x16_bf16 v[96:111], v[202:205], v[140:143], v[96:111]
	v_mov_b32_e32 v64, v254
	v_fmamk_f32 v65, v208, 0x3f800000, v254
	v_fmamk_f32 v66, v208, 0x40000000, v254
	v_fmamk_f32 v67, v208, 0x40400000, v254
	v_fmamk_f32 v68, v208, 0x41000000, v254
	v_fmamk_f32 v69, v208, 0x41100000, v254
	v_fmamk_f32 v70, v208, 0x41200000, v254
	v_fmamk_f32 v71, v208, 0x41300000, v254
	v_mfma_f32_32x32x16_bf16 v[96:111], v[194:197], v[136:139], v[96:111]
	v_fmamk_f32 v72, v208, 0x41800000, v254
	v_fmamk_f32 v73, v208, 0x41880000, v254
	v_fmamk_f32 v74, v208, 0x41900000, v254
	v_fmamk_f32 v75, v208, 0x41980000, v254
	v_fmamk_f32 v76, v208, 0x41c00000, v254
	v_fmamk_f32 v77, v208, 0x41c80000, v254
	v_mfma_f32_32x32x16_bf16 v[96:111], v[186:189], v[132:135], v[96:111]
	v_fmamk_f32 v78, v208, 0x41d00000, v254
	v_fmamk_f32 v79, v208, 0x41d80000, v254
	ds_read_b64_tr_b16 v[182:183], v158 offset:32768
	ds_read_b64_tr_b16 v[184:185], v158 offset:34816
	ds_read_b64_tr_b16 v[178:179], v159 offset:32768
	ds_read_b64_tr_b16 v[180:181], v159 offset:34816
	ds_read_b64_tr_b16 v[148:149], v160 offset:32768
	ds_read_b64_tr_b16 v[150:151], v160 offset:34816
	ds_read_b64_tr_b16 v[152:153], v161 offset:32768
	ds_read_b64_tr_b16 v[154:155], v161 offset:34816
	s_waitcnt lgkmcnt(8)
	v_mfma_f32_32x32x16_bf16 v[80:95], v[198:201], v[144:147], v[64:79]
	v_exp_f32_e32 v96, v96
	v_exp_f32_e32 v97, v97
	v_exp_f32_e32 v98, v98
	v_exp_f32_e32 v99, v99
	v_mfma_f32_32x32x16_bf16 v[80:95], v[190:193], v[140:143], v[80:95]
	v_exp_f32_e32 v100, v100
	v_exp_f32_e32 v101, v101
	v_exp_f32_e32 v102, v102
	v_exp_f32_e32 v103, v103
	v_mfma_f32_32x32x16_bf16 v[80:95], v[246:249], v[136:139], v[80:95]
	v_exp_f32_e32 v104, v104
	v_exp_f32_e32 v105, v105
	v_exp_f32_e32 v106, v106
	v_exp_f32_e32 v107, v107
	v_mfma_f32_32x32x16_bf16 v[80:95], v[250:253], v[132:135], v[80:95]
	v_exp_f32_e32 v108, v108
	v_exp_f32_e32 v109, v109
	v_exp_f32_e32 v110, v110
	v_exp_f32_e32 v111, v111
	s_nop 3
	s_cmp_le_i32 s72, s101
	s_cbranch_scc0 .Lmask_blk
